# lever 7.3/T21 extended: mem-attention unit RMW epilogue loads+stores widened via permlane32_swap (16+16 dwordx2 -> 8+8 dwordx4)
# speedup vs baseline: 1.0125x; 1.0023x over previous
; #define GAS __attribute__((address_space(1)))
; template <int DQK, int DV, int RH, bool NEGM> ...
;     ...
; #pragma unroll
;     for (int hh = 0; hh < RH; ++hh) {
;         float l = (lacc[hh][0] + lacc[hh][1]) + (lacc[hh][2] + lacc[hh][3]); l += __shfl_xor(l, 32);
;         const float inv = 1.f / l;
;         const size_t ro = (size_t)(wid * 32 * RH + hh * 32 + r32) * zpitch;
; #pragma unroll
;         for (int dt = 0; dt < DV / 32; ++dt)
; #pragma unroll
;             for (int i = 0; i < 4; ++i) {
;                 const int c = dt * 32 + 8 * i + 4 * hi;
;                 const u32x2 zw = *(const GAS u32x2*)(ZI + ro + c);
.LBB0_897:
	v_exp_f32_e32 v95, v80
	v_add_u32_e32 v80, s36, v179
	v_exp_f32_e32 v93, v101
	v_exp_f32_e32 v101, v81
	v_add_u32_e32 v81, 0x8800, v80
	ds_read2_b64 v[110:113], v81 offset1:2
	v_exp_f32_e32 v91, v100
	v_exp_f32_e32 v90, v96
	v_exp_f32_e32 v92, v97
	v_exp_f32_e32 v97, v98
	v_exp_f32_e32 v99, v99
	v_exp_f32_e32 v96, v102
	v_exp_f32_e32 v98, v103
	v_cvt_pk_bf16_f32 v76, v91, v93
	v_cvt_pk_bf16_f32 v77, v90, v92
	v_cvt_pk_bf16_f32 v78, v97, v99
	v_cvt_pk_bf16_f32 v79, v96, v98
	ds_read2_b64 v[114:117], v81 offset0:4 offset1:6
	v_exp_f32_e32 v94, v82
	s_waitcnt lgkmcnt(1)
	v_mfma_f32_32x32x16_bf16 v[48:63], v[110:113], v[76:79], v[48:63]
	v_exp_f32_e32 v100, v83
	v_exp_f32_e32 v107, v84
	v_exp_f32_e32 v109, v85
	v_exp_f32_e32 v83, v104
	v_exp_f32_e32 v85, v105
	v_exp_f32_e32 v82, v72
	v_exp_f32_e32 v84, v73
	v_exp_f32_e32 v105, v74
	v_exp_f32_e32 v103, v75
	v_exp_f32_e32 v104, v70
	v_exp_f32_e32 v102, v71
	v_cvt_pk_bf16_f32 v72, v83, v85
	v_cvt_pk_bf16_f32 v73, v82, v84
	v_cvt_pk_bf16_f32 v74, v105, v103
	v_cvt_pk_bf16_f32 v75, v104, v102
	ds_read2_b64 v[118:121], v81 offset0:8 offset1:10
	v_exp_f32_e32 v106, v86
	s_waitcnt lgkmcnt(1)
	v_mfma_f32_32x32x16_bf16 v[48:63], v[114:117], v[72:75], v[48:63]
	v_exp_f32_e32 v108, v87
	v_exp_f32_e32 v87, v88
	v_exp_f32_e32 v86, v68
	v_exp_f32_e32 v88, v69
	v_cvt_pk_bf16_f32 v68, v95, v101
	v_cvt_pk_bf16_f32 v69, v94, v100
	v_cvt_pk_bf16_f32 v70, v107, v109
	v_cvt_pk_bf16_f32 v71, v106, v108
	ds_read2_b64 v[114:117], v81 offset0:12 offset1:14
	v_exp_f32_e32 v89, v89
	s_waitcnt lgkmcnt(1)
	v_mfma_f32_32x32x16_bf16 v[48:63], v[118:121], v[68:71], v[48:63]
	v_exp_f32_e32 v111, v64
	v_exp_f32_e32 v113, v65
	v_exp_f32_e32 v110, v66
	v_exp_f32_e32 v112, v67
	v_cvt_pk_bf16_f32 v64, v87, v89
	v_cvt_pk_bf16_f32 v65, v86, v88
	v_cvt_pk_bf16_f32 v66, v111, v113
	v_cvt_pk_bf16_f32 v67, v110, v112
	v_add_u32_e32 v81, 0x9800, v80
	v_pk_add_f32 v[90:91], v[90:91], v[94:95]
	s_waitcnt lgkmcnt(0)
	v_mfma_f32_32x32x16_bf16 v[48:63], v[114:117], v[64:67], v[48:63]
	ds_read2_b64 v[114:117], v81 offset0:32 offset1:34
	v_add_f32_e64 v92, v92, v100
	v_add_f32_e64 v93, v93, v101
	v_add_f32_e64 v94, v96, v106
	v_add_f32_e64 v95, v97, v107
	v_pk_add_f32 v[96:97], v[98:99], v[108:109]
	v_pk_add_f32 v[90:91], v[150:151], v[90:91]
	v_pk_add_f32 v[92:93], v[148:149], v[92:93]
	v_pk_add_f32 v[82:83], v[82:83], v[86:87]
	s_waitcnt lgkmcnt(0)
	v_mfma_f32_32x32x16_bf16 v[32:47], v[114:117], v[76:79], v[32:47]
	ds_read2_b64 v[114:117], v81 offset0:36 offset1:38
	v_add_f32_e64 v84, v84, v88
	v_add_f32_e64 v85, v85, v89
	v_add_f32_e64 v90, v94, v90
	v_add_f32_e64 v91, v95, v91
	v_pk_add_f32 v[86:87], v[104:105], v[110:111]
	v_pk_add_f32 v[88:89], v[102:103], v[112:113]
	s_add_i32 s87, s87, s18
	s_add_i32 s88, s88, s20
	s_waitcnt lgkmcnt(0)
	v_mfma_f32_32x32x16_bf16 v[32:47], v[114:117], v[72:75], v[32:47]
	ds_read2_b64 v[114:117], v81 offset0:40 offset1:42
	s_cmpk_gt_i32 s87, 0x1ff
	s_waitcnt lgkmcnt(0)
	v_mfma_f32_32x32x16_bf16 v[32:47], v[114:117], v[68:71], v[32:47]
	ds_read2_b64 v[114:117], v81 offset0:44 offset1:46
	v_add_u32_e32 v81, 0xa800, v80
	v_add_u32_e32 v80, 0xb800, v80
	s_waitcnt lgkmcnt(0)
	v_mfma_f32_32x32x16_bf16 v[32:47], v[114:117], v[64:67], v[32:47]
	ds_read2_b64 v[114:117], v81 offset0:64 offset1:66
	ds_read2_b64 v[118:121], v81 offset0:68 offset1:70
	s_waitcnt lgkmcnt(1)
	v_mfma_f32_32x32x16_bf16 v[16:31], v[114:117], v[76:79], v[16:31]
	ds_read2_b64 v[114:117], v81 offset0:72 offset1:74
	ds_read2_b64 v[122:125], v81 offset0:76 offset1:78
	ds_read2_b64 v[126:129], v80 offset0:96 offset1:98
	ds_read2_b64 v[130:133], v80 offset0:100 offset1:102
	ds_read2_b64 v[134:137], v80 offset0:104 offset1:106
	ds_read2_b64 v[138:141], v80 offset0:108 offset1:110
	v_lshlrev_b32_e32 v80, 3, v178
	v_ashrrev_i32_e32 v81, 31, v80
	v_lshl_add_u64 v[80:81], v[80:81], 1, v[146:147]
	s_waitcnt lgkmcnt(0)
	s_barrier
	global_load_dwordx4 v[98:101], v[80:81], off offset:2048
	global_load_dwordx4 v[102:105], v[80:81], off offset:2080
	v_mfma_f32_32x32x16_bf16 v[16:31], v[118:121], v[72:75], v[16:31]
	global_load_dwordx4 v[106:109], v[80:81], off offset:2112
	v_mfma_f32_32x32x16_bf16 v[0:15], v[126:129], v[76:79], v[0:15]
	v_add_f32_e64 v76, v96, v92
	v_add_f32_e64 v77, v97, v93
	v_add_f32_e64 v78, v82, v90
	v_add_f32_e64 v79, v83, v91
	v_add_f32_e64 v76, v84, v76
	v_add_f32_e64 v77, v85, v77
	v_pk_add_f32 v[78:79], v[86:87], v[78:79]
	v_pk_add_f32 v[76:77], v[88:89], v[76:77]
	global_load_dwordx4 v[110:113], v[80:81], off offset:2144
	v_pk_add_f32 v[76:77], v[76:77], v[78:79]
	v_mfma_f32_32x32x16_bf16 v[16:31], v[114:117], v[68:71], v[16:31]
	global_load_dwordx4 v[118:121], v[80:81], off offset:2176
	v_add_f32_e32 v76, v76, v77
	ds_bpermute_b32 v77, v153, v76
	v_mfma_f32_32x32x16_bf16 v[0:15], v[130:133], v[72:75], v[0:15]
	s_waitcnt lgkmcnt(0)
	v_add_f32_e32 v74, v76, v77
	v_div_scale_f32 v75, s[6:7], v74, v74, 1.0
	v_rcp_f32_e32 v76, v75
	global_load_dwordx4 v[126:129], v[80:81], off offset:2208
	v_mfma_f32_32x32x16_bf16 v[0:15], v[134:137], v[68:71], v[0:15]
	v_fma_f32 v68, -v75, v76, 1.0
	v_fmac_f32_e32 v76, v68, v76
	v_div_scale_f32 v70, vcc, 1.0, v74, 1.0
	v_mul_f32_e32 v71, v70, v76
	v_fma_f32 v77, -v75, v71, v70
	global_load_dwordx4 v[114:117], v[80:81], off offset:2240
	v_fmac_f32_e32 v71, v77, v76
	v_mfma_f32_32x32x16_bf16 v[16:31], v[122:125], v[64:67], v[16:31]
	v_mfma_f32_32x32x16_bf16 v[0:15], v[138:141], v[64:67], v[0:15]
	global_load_dwordx4 v[130:133], v[80:81], off offset:2272
	v_fma_f32 v64, -v75, v71, v70
	v_div_fmas_f32 v64, v64, v76, v71
	v_div_fixup_f32 v64, v64, v74, 1.0
	s_waitcnt vmcnt(7)
; #define GAS __attribute__((address_space(1)))
; __device__ __forceinline__ float bf_lo(unsigned w) { return __uint_as_float(w << 16); }
; __device__ __forceinline__ float bf_hi(unsigned w) { return __uint_as_float(w & 0xffff0000u); }
; template <int DQK, int DV, int RH, bool NEGM> ...
;     ...
; #pragma unroll
;         for (int dt = 0; dt < DV / 32; ++dt)
; #pragma unroll
;             for (int i = 0; i < 4; ++i) {
;                 const int c = dt * 32 + 8 * i + 4 * hi;
;                 const u32x2 zw = *(const GAS u32x2*)(ZI + ro + c);
;                 u32x2 w;
;                 w.x = pk2(o[hh][dt][4 * i + 0] * inv * bf_lo(zw.x), o[hh][dt][4 * i + 1] * inv * bf_hi(zw.x));
;                 w.y = pk2(o[hh][dt][4 * i + 2] * inv * bf_lo(zw.y), o[hh][dt][4 * i + 3] * inv * bf_hi(zw.y));
;                 *(GAS u32x2*)(ZO + ro + c) = w;
;             }
	v_permlane32_swap_b32_e32 v98, v100
	v_permlane32_swap_b32_e32 v99, v101
	v_pk_mul_f32 v[48:49], v[48:49], v[64:65] op_sel_hi:[1,0]
	v_pk_mul_f32 v[50:51], v[50:51], v[64:65] op_sel_hi:[1,0]
	v_lshlrev_b32_e32 v66, 16, v98
	v_and_b32_e32 v67, 0xffff0000, v98
	v_lshlrev_b32_e32 v70, 16, v99
	v_and_b32_e32 v71, 0xffff0000, v99
	v_pk_mul_f32 v[48:49], v[48:49], v[66:67]
	v_pk_mul_f32 v[50:51], v[50:51], v[70:71]
	v_pk_mul_f32 v[52:53], v[52:53], v[64:65] op_sel_hi:[1,0]
	v_pk_mul_f32 v[54:55], v[54:55], v[64:65] op_sel_hi:[1,0]
	v_lshlrev_b32_e32 v68, 16, v100
	v_and_b32_e32 v69, 0xffff0000, v100
	v_lshlrev_b32_e32 v72, 16, v101
	v_and_b32_e32 v73, 0xffff0000, v101
	v_pk_mul_f32 v[52:53], v[52:53], v[68:69]
	v_pk_mul_f32 v[54:55], v[54:55], v[72:73]
	v_cvt_pk_bf16_f32 v48, v48, v49
	v_cvt_pk_bf16_f32 v49, v50, v51
	v_cvt_pk_bf16_f32 v50, v52, v53
	v_cvt_pk_bf16_f32 v51, v54, v55
	s_nop 1
	v_permlane32_swap_b32_e32 v48, v50
	v_permlane32_swap_b32_e32 v49, v51
	global_store_dwordx4 v[80:81], v[48:51], off offset:2048
	s_waitcnt vmcnt(7)
	v_permlane32_swap_b32_e32 v102, v104
	v_permlane32_swap_b32_e32 v103, v105
	v_pk_mul_f32 v[56:57], v[56:57], v[64:65] op_sel_hi:[1,0]
	v_pk_mul_f32 v[58:59], v[58:59], v[64:65] op_sel_hi:[1,0]
	v_lshlrev_b32_e32 v66, 16, v102
	v_and_b32_e32 v67, 0xffff0000, v102
	v_lshlrev_b32_e32 v70, 16, v103
	v_and_b32_e32 v71, 0xffff0000, v103
	v_pk_mul_f32 v[56:57], v[56:57], v[66:67]
	v_pk_mul_f32 v[58:59], v[58:59], v[70:71]
	v_pk_mul_f32 v[60:61], v[60:61], v[64:65] op_sel_hi:[1,0]
	v_pk_mul_f32 v[62:63], v[62:63], v[64:65] op_sel_hi:[1,0]
	v_lshlrev_b32_e32 v68, 16, v104
	v_and_b32_e32 v69, 0xffff0000, v104
	v_lshlrev_b32_e32 v72, 16, v105
	v_and_b32_e32 v73, 0xffff0000, v105
	v_pk_mul_f32 v[60:61], v[60:61], v[68:69]
	v_pk_mul_f32 v[62:63], v[62:63], v[72:73]
	v_cvt_pk_bf16_f32 v56, v56, v57
	v_cvt_pk_bf16_f32 v57, v58, v59
	v_cvt_pk_bf16_f32 v58, v60, v61
	v_cvt_pk_bf16_f32 v59, v62, v63
	s_nop 1
	v_permlane32_swap_b32_e32 v56, v58
	v_permlane32_swap_b32_e32 v57, v59
	global_store_dwordx4 v[80:81], v[56:59], off offset:2080
	s_waitcnt vmcnt(7)
	v_permlane32_swap_b32_e32 v106, v108
	v_permlane32_swap_b32_e32 v107, v109
	v_pk_mul_f32 v[32:33], v[32:33], v[64:65] op_sel_hi:[1,0]
	v_pk_mul_f32 v[34:35], v[34:35], v[64:65] op_sel_hi:[1,0]
	v_lshlrev_b32_e32 v66, 16, v106
	v_and_b32_e32 v67, 0xffff0000, v106
	v_lshlrev_b32_e32 v70, 16, v107
	v_and_b32_e32 v71, 0xffff0000, v107
	v_pk_mul_f32 v[32:33], v[32:33], v[66:67]
	v_pk_mul_f32 v[34:35], v[34:35], v[70:71]
	v_pk_mul_f32 v[36:37], v[36:37], v[64:65] op_sel_hi:[1,0]
	v_pk_mul_f32 v[38:39], v[38:39], v[64:65] op_sel_hi:[1,0]
	v_lshlrev_b32_e32 v68, 16, v108
	v_and_b32_e32 v69, 0xffff0000, v108
	v_lshlrev_b32_e32 v72, 16, v109
	v_and_b32_e32 v73, 0xffff0000, v109
	v_pk_mul_f32 v[36:37], v[36:37], v[68:69]
	v_pk_mul_f32 v[38:39], v[38:39], v[72:73]
	v_cvt_pk_bf16_f32 v32, v32, v33
	v_cvt_pk_bf16_f32 v33, v34, v35
	v_cvt_pk_bf16_f32 v34, v36, v37
	v_cvt_pk_bf16_f32 v35, v38, v39
	s_nop 1
	v_permlane32_swap_b32_e32 v32, v34
	v_permlane32_swap_b32_e32 v33, v35
	global_store_dwordx4 v[80:81], v[32:35], off offset:2112
	s_waitcnt vmcnt(7)
	v_permlane32_swap_b32_e32 v110, v112
	v_permlane32_swap_b32_e32 v111, v113
	v_pk_mul_f32 v[40:41], v[40:41], v[64:65] op_sel_hi:[1,0]
	v_pk_mul_f32 v[42:43], v[42:43], v[64:65] op_sel_hi:[1,0]
	v_lshlrev_b32_e32 v66, 16, v110
	v_and_b32_e32 v67, 0xffff0000, v110
	v_lshlrev_b32_e32 v70, 16, v111
	v_and_b32_e32 v71, 0xffff0000, v111
	v_pk_mul_f32 v[40:41], v[40:41], v[66:67]
	v_pk_mul_f32 v[42:43], v[42:43], v[70:71]
	v_pk_mul_f32 v[44:45], v[44:45], v[64:65] op_sel_hi:[1,0]
	v_pk_mul_f32 v[46:47], v[46:47], v[64:65] op_sel_hi:[1,0]
	v_lshlrev_b32_e32 v68, 16, v112
	v_and_b32_e32 v69, 0xffff0000, v112
	v_lshlrev_b32_e32 v72, 16, v113
	v_and_b32_e32 v73, 0xffff0000, v113
	v_pk_mul_f32 v[44:45], v[44:45], v[68:69]
	v_pk_mul_f32 v[46:47], v[46:47], v[72:73]
	v_cvt_pk_bf16_f32 v40, v40, v41
	v_cvt_pk_bf16_f32 v41, v42, v43
	v_cvt_pk_bf16_f32 v42, v44, v45
	v_cvt_pk_bf16_f32 v43, v46, v47
	s_nop 1
	v_permlane32_swap_b32_e32 v40, v42
	v_permlane32_swap_b32_e32 v41, v43
	global_store_dwordx4 v[80:81], v[40:43], off offset:2144
	s_waitcnt vmcnt(7)
; #define GAS __attribute__((address_space(1)))
; __device__ __forceinline__ float bf_lo(unsigned w) { return __uint_as_float(w << 16); }
; __device__ __forceinline__ float bf_hi(unsigned w) { return __uint_as_float(w & 0xffff0000u); }
; template <int DQK, int DV, int RH, bool NEGM> ...
;     ...
; #pragma unroll
;         for (int dt = 0; dt < DV / 32; ++dt)
; #pragma unroll
;             for (int i = 0; i < 4; ++i) {
;                 const int c = dt * 32 + 8 * i + 4 * hi;
;                 const u32x2 zw = *(const GAS u32x2*)(ZI + ro + c);
;                 u32x2 w;
;                 w.x = pk2(o[hh][dt][4 * i + 0] * inv * bf_lo(zw.x), o[hh][dt][4 * i + 1] * inv * bf_hi(zw.x));
;                 w.y = pk2(o[hh][dt][4 * i + 2] * inv * bf_lo(zw.y), o[hh][dt][4 * i + 3] * inv * bf_hi(zw.y));
;                 *(GAS u32x2*)(ZO + ro + c) = w;
;             }
;     }
;     __syncthreads();
	v_permlane32_swap_b32_e32 v118, v120
	v_permlane32_swap_b32_e32 v119, v121
	v_pk_mul_f32 v[16:17], v[16:17], v[64:65] op_sel_hi:[1,0]
	v_pk_mul_f32 v[18:19], v[18:19], v[64:65] op_sel_hi:[1,0]
	v_lshlrev_b32_e32 v66, 16, v118
	v_and_b32_e32 v67, 0xffff0000, v118
	v_lshlrev_b32_e32 v70, 16, v119
	v_and_b32_e32 v71, 0xffff0000, v119
	v_pk_mul_f32 v[16:17], v[16:17], v[66:67]
	v_pk_mul_f32 v[18:19], v[18:19], v[70:71]
	v_pk_mul_f32 v[20:21], v[20:21], v[64:65] op_sel_hi:[1,0]
	v_pk_mul_f32 v[22:23], v[22:23], v[64:65] op_sel_hi:[1,0]
	v_lshlrev_b32_e32 v68, 16, v120
	v_and_b32_e32 v69, 0xffff0000, v120
	v_lshlrev_b32_e32 v72, 16, v121
	v_and_b32_e32 v73, 0xffff0000, v121
	v_pk_mul_f32 v[20:21], v[20:21], v[68:69]
	v_pk_mul_f32 v[22:23], v[22:23], v[72:73]
	v_cvt_pk_bf16_f32 v16, v16, v17
	v_cvt_pk_bf16_f32 v17, v18, v19
	v_cvt_pk_bf16_f32 v18, v20, v21
	v_cvt_pk_bf16_f32 v19, v22, v23
	s_nop 1
	v_permlane32_swap_b32_e32 v16, v18
	v_permlane32_swap_b32_e32 v17, v19
	global_store_dwordx4 v[80:81], v[16:19], off offset:2176
	s_waitcnt vmcnt(7)
	v_permlane32_swap_b32_e32 v126, v128
	v_permlane32_swap_b32_e32 v127, v129
	v_pk_mul_f32 v[24:25], v[24:25], v[64:65] op_sel_hi:[1,0]
	v_pk_mul_f32 v[26:27], v[26:27], v[64:65] op_sel_hi:[1,0]
	v_lshlrev_b32_e32 v66, 16, v126
	v_and_b32_e32 v67, 0xffff0000, v126
	v_lshlrev_b32_e32 v70, 16, v127
	v_and_b32_e32 v71, 0xffff0000, v127
	v_pk_mul_f32 v[24:25], v[24:25], v[66:67]
	v_pk_mul_f32 v[26:27], v[26:27], v[70:71]
	v_pk_mul_f32 v[28:29], v[28:29], v[64:65] op_sel_hi:[1,0]
	v_pk_mul_f32 v[30:31], v[30:31], v[64:65] op_sel_hi:[1,0]
	v_lshlrev_b32_e32 v68, 16, v128
	v_and_b32_e32 v69, 0xffff0000, v128
	v_lshlrev_b32_e32 v72, 16, v129
	v_and_b32_e32 v73, 0xffff0000, v129
	v_pk_mul_f32 v[28:29], v[28:29], v[68:69]
	v_pk_mul_f32 v[30:31], v[30:31], v[72:73]
	v_cvt_pk_bf16_f32 v24, v24, v25
	v_cvt_pk_bf16_f32 v25, v26, v27
	v_cvt_pk_bf16_f32 v26, v28, v29
	v_cvt_pk_bf16_f32 v27, v30, v31
	s_nop 1
	v_permlane32_swap_b32_e32 v24, v26
	v_permlane32_swap_b32_e32 v25, v27
	global_store_dwordx4 v[80:81], v[24:27], off offset:2208
	s_waitcnt vmcnt(7)
	v_permlane32_swap_b32_e32 v114, v116
	v_permlane32_swap_b32_e32 v115, v117
	v_pk_mul_f32 v[0:1], v[0:1], v[64:65] op_sel_hi:[1,0]
	v_pk_mul_f32 v[2:3], v[2:3], v[64:65] op_sel_hi:[1,0]
	v_lshlrev_b32_e32 v66, 16, v114
	v_and_b32_e32 v67, 0xffff0000, v114
	v_lshlrev_b32_e32 v70, 16, v115
	v_and_b32_e32 v71, 0xffff0000, v115
	v_pk_mul_f32 v[0:1], v[0:1], v[66:67]
	v_pk_mul_f32 v[2:3], v[2:3], v[70:71]
	v_pk_mul_f32 v[4:5], v[4:5], v[64:65] op_sel_hi:[1,0]
	v_pk_mul_f32 v[6:7], v[6:7], v[64:65] op_sel_hi:[1,0]
	v_lshlrev_b32_e32 v68, 16, v116
	v_and_b32_e32 v69, 0xffff0000, v116
	v_lshlrev_b32_e32 v72, 16, v117
	v_and_b32_e32 v73, 0xffff0000, v117
	v_pk_mul_f32 v[4:5], v[4:5], v[68:69]
	v_pk_mul_f32 v[6:7], v[6:7], v[72:73]
	v_cvt_pk_bf16_f32 v0, v0, v1
	v_cvt_pk_bf16_f32 v1, v2, v3
	v_cvt_pk_bf16_f32 v2, v4, v5
	v_cvt_pk_bf16_f32 v3, v6, v7
	s_nop 1
	v_permlane32_swap_b32_e32 v0, v2
	v_permlane32_swap_b32_e32 v1, v3
	global_store_dwordx4 v[80:81], v[0:3], off offset:2240
	s_waitcnt vmcnt(7)
	v_permlane32_swap_b32_e32 v130, v132
	v_permlane32_swap_b32_e32 v131, v133
	v_pk_mul_f32 v[8:9], v[8:9], v[64:65] op_sel_hi:[1,0]
	v_pk_mul_f32 v[10:11], v[10:11], v[64:65] op_sel_hi:[1,0]
	v_lshlrev_b32_e32 v66, 16, v130
	v_and_b32_e32 v67, 0xffff0000, v130
	v_lshlrev_b32_e32 v70, 16, v131
	v_and_b32_e32 v71, 0xffff0000, v131
	v_pk_mul_f32 v[8:9], v[8:9], v[66:67]
	v_pk_mul_f32 v[10:11], v[10:11], v[70:71]
	v_pk_mul_f32 v[12:13], v[12:13], v[64:65] op_sel_hi:[1,0]
	v_pk_mul_f32 v[14:15], v[14:15], v[64:65] op_sel_hi:[1,0]
	v_lshlrev_b32_e32 v68, 16, v132
	v_and_b32_e32 v69, 0xffff0000, v132
	v_lshlrev_b32_e32 v72, 16, v133
	v_and_b32_e32 v73, 0xffff0000, v133
	v_pk_mul_f32 v[12:13], v[12:13], v[68:69]
	v_pk_mul_f32 v[14:15], v[14:15], v[72:73]
	v_cvt_pk_bf16_f32 v8, v8, v9
	v_cvt_pk_bf16_f32 v9, v10, v11
	v_cvt_pk_bf16_f32 v10, v12, v13
	v_cvt_pk_bf16_f32 v11, v14, v15
	s_nop 1
	v_permlane32_swap_b32_e32 v8, v10
	v_permlane32_swap_b32_e32 v9, v11
	global_store_dwordx4 v[80:81], v[8:11], off offset:2272
	s_barrier
	s_cbranch_scc1 .LBB0_930
